# v50: split-K tail tile: waves 4-7 (rows beyond T) neither publish nor read partial slabs (v47 base)
# speedup vs baseline: 1.0041x; 1.0041x over previous
.LBB0_627:
	v_readfirstlane_b32 s98, v208
	s_mov_b64 s[100:101], exec
	s_bitcmp1_b32 s98, 8
	s_cbranch_scc0 .Lskh0_a
	s_mov_b64 exec, 0
.Lskh0_a:
	s_mul_i32 s41, s4, 0x160000
	s_mul_hi_i32 s40, s4, 0x160000
	s_add_u32 s2, s65, s41
	v_readlane_b32 s0, v239, 20
	s_addc_u32 s3, s0, s40
	s_lshl_b32 s14, s37, 15
	s_lshl_b64 s[0:1], s[14:15], 2
	s_waitcnt vmcnt(7)
	v_mov_b32_e32 v130, v208
	s_add_u32 s0, s2, s0
	s_addc_u32 s1, s3, s1
	v_ashrrev_i32_e32 v131, 31, v130
	v_lshl_add_u64 v[132:133], v[130:131], 2, s[0:1]
	s_movk_i32 s0, 0x1000
	s_waitcnt vmcnt(3)
	v_add_co_u32_e32 v134, vcc, s0, v132
	s_movk_i32 s0, 0x2000
	s_nop 0
	v_addc_co_u32_e32 v135, vcc, 0, v133, vcc
	v_add_co_u32_e32 v136, vcc, s0, v132
	s_movk_i32 s0, 0x3000
	s_nop 0
	v_addc_co_u32_e32 v137, vcc, 0, v133, vcc
	global_store_dword v[132:133], v114, off
	global_store_dword v[132:133], v115, off offset:2048
	global_store_dword v[136:137], v116, off offset:-4096
	global_store_dword v[134:135], v117, off offset:2048
	global_store_dword v[136:137], v118, off
	global_store_dword v[136:137], v119, off offset:2048
	v_add_co_u32_e32 v134, vcc, s0, v132
	s_movk_i32 s0, 0x4000
	s_nop 0
	v_addc_co_u32_e32 v135, vcc, 0, v133, vcc
	v_add_co_u32_e32 v136, vcc, s0, v132
	s_movk_i32 s0, 0x5000
	s_nop 0
	v_addc_co_u32_e32 v137, vcc, 0, v133, vcc
	global_store_dword v[136:137], v120, off offset:-4096
	global_store_dword v[134:135], v121, off offset:2048
	global_store_dword v[136:137], v122, off
	global_store_dword v[136:137], v123, off offset:2048
	v_add_co_u32_e32 v134, vcc, s0, v132
	s_movk_i32 s0, 0x6000
	s_nop 0
	v_addc_co_u32_e32 v135, vcc, 0, v133, vcc
	v_add_co_u32_e32 v136, vcc, s0, v132
	s_movk_i32 s0, 0x7000
	s_nop 0
	v_addc_co_u32_e32 v137, vcc, 0, v133, vcc
	global_store_dword v[136:137], v124, off offset:-4096
	global_store_dword v[134:135], v125, off offset:2048
	global_store_dword v[136:137], v126, off
	global_store_dword v[136:137], v127, off offset:2048
	v_add_co_u32_e32 v134, vcc, s0, v132
	s_mov_b32 s0, 0x8000
	s_nop 0
	v_addc_co_u32_e32 v135, vcc, 0, v133, vcc
	v_add_co_u32_e32 v136, vcc, s0, v132
	s_mov_b32 s0, 0x9000
	s_nop 0
	v_addc_co_u32_e32 v137, vcc, 0, v133, vcc
	global_store_dword v[136:137], v128, off offset:-4096
	global_store_dword v[134:135], v129, off offset:2048
	global_store_dword v[136:137], v98, off
	global_store_dword v[136:137], v99, off offset:2048
	v_add_co_u32_e32 v134, vcc, s0, v132
	s_mov_b32 s0, 0xa000
	s_nop 0
	v_addc_co_u32_e32 v135, vcc, 0, v133, vcc
	v_add_co_u32_e32 v136, vcc, s0, v132
	s_mov_b32 s0, 0xb000
	s_nop 0
	v_addc_co_u32_e32 v137, vcc, 0, v133, vcc
	global_store_dword v[136:137], v100, off offset:-4096
	global_store_dword v[134:135], v101, off offset:2048
	global_store_dword v[136:137], v102, off
	global_store_dword v[136:137], v103, off offset:2048
	v_add_co_u32_e32 v134, vcc, s0, v132
	s_mov_b32 s0, 0xc000
	s_nop 0
	v_addc_co_u32_e32 v135, vcc, 0, v133, vcc
	v_add_co_u32_e32 v136, vcc, s0, v132
	s_mov_b32 s0, 0xd000
	s_nop 0
	v_addc_co_u32_e32 v137, vcc, 0, v133, vcc
	global_store_dword v[136:137], v104, off offset:-4096
	global_store_dword v[134:135], v105, off offset:2048
	global_store_dword v[136:137], v106, off
	global_store_dword v[136:137], v107, off offset:2048
	v_add_co_u32_e32 v134, vcc, s0, v132
	s_mov_b32 s0, 0xe000
	s_nop 0
	v_addc_co_u32_e32 v135, vcc, 0, v133, vcc
	v_add_co_u32_e32 v136, vcc, s0, v132
	s_mov_b32 s0, 0xf000
	s_nop 0
	v_addc_co_u32_e32 v137, vcc, 0, v133, vcc
	global_store_dword v[136:137], v108, off offset:-4096
	global_store_dword v[134:135], v109, off offset:2048
	global_store_dword v[136:137], v110, off
	global_store_dword v[136:137], v111, off offset:2048
	v_add_co_u32_e32 v134, vcc, s0, v132
	s_mov_b32 s0, 0x10000
	s_nop 0
	v_addc_co_u32_e32 v135, vcc, 0, v133, vcc
	v_add_co_u32_e32 v136, vcc, s0, v132
	s_mov_b32 s0, 0x11000
	s_nop 0
	v_addc_co_u32_e32 v137, vcc, 0, v133, vcc
	global_store_dword v[136:137], v112, off offset:-4096
	global_store_dword v[134:135], v113, off offset:2048
	global_store_dword v[136:137], v82, off
	global_store_dword v[136:137], v83, off offset:2048
	v_add_co_u32_e32 v134, vcc, s0, v132
	s_mov_b32 s0, 0x12000
	s_nop 0
	v_addc_co_u32_e32 v135, vcc, 0, v133, vcc
	v_add_co_u32_e32 v136, vcc, s0, v132
	s_mov_b32 s0, 0x13000
	s_nop 0
	v_addc_co_u32_e32 v137, vcc, 0, v133, vcc
	global_store_dword v[136:137], v84, off offset:-4096
	global_store_dword v[134:135], v85, off offset:2048
	global_store_dword v[136:137], v86, off
	global_store_dword v[136:137], v87, off offset:2048
	v_add_co_u32_e32 v134, vcc, s0, v132
	s_mov_b32 s0, 0x14000
	s_nop 0
	v_addc_co_u32_e32 v135, vcc, 0, v133, vcc
	v_add_co_u32_e32 v136, vcc, s0, v132
	s_mov_b32 s0, 0x15000
	s_nop 0
	v_addc_co_u32_e32 v137, vcc, 0, v133, vcc
	global_store_dword v[136:137], v88, off offset:-4096
	global_store_dword v[134:135], v89, off offset:2048
	global_store_dword v[136:137], v90, off
	global_store_dword v[136:137], v91, off offset:2048
	v_add_co_u32_e32 v134, vcc, s0, v132
	s_mov_b32 s0, 0x16000
	s_nop 0
	v_addc_co_u32_e32 v135, vcc, 0, v133, vcc
	v_add_co_u32_e32 v136, vcc, s0, v132
	s_mov_b32 s0, 0x17000
	s_nop 0
	v_addc_co_u32_e32 v137, vcc, 0, v133, vcc
	global_store_dword v[136:137], v92, off offset:-4096
	global_store_dword v[134:135], v93, off offset:2048
	global_store_dword v[136:137], v94, off
	global_store_dword v[136:137], v95, off offset:2048
	v_add_co_u32_e32 v134, vcc, s0, v132
	s_mov_b32 s0, 0x18000
	s_nop 0
	v_addc_co_u32_e32 v135, vcc, 0, v133, vcc
	v_add_co_u32_e32 v136, vcc, s0, v132
	s_mov_b32 s0, 0x19000
	s_nop 0
	v_addc_co_u32_e32 v137, vcc, 0, v133, vcc
	global_store_dword v[136:137], v96, off offset:-4096
	global_store_dword v[134:135], v97, off offset:2048
	global_store_dword v[136:137], v66, off
	global_store_dword v[136:137], v67, off offset:2048
	v_add_co_u32_e32 v134, vcc, s0, v132
	s_mov_b32 s0, 0x1a000
	s_nop 0
	v_addc_co_u32_e32 v135, vcc, 0, v133, vcc
	v_add_co_u32_e32 v136, vcc, s0, v132
	s_mov_b32 s0, 0x1b000
	s_nop 0
	v_addc_co_u32_e32 v137, vcc, 0, v133, vcc
	global_store_dword v[136:137], v68, off offset:-4096
	global_store_dword v[134:135], v69, off offset:2048
	global_store_dword v[136:137], v70, off
	global_store_dword v[136:137], v71, off offset:2048
	v_add_co_u32_e32 v134, vcc, s0, v132
	s_mov_b32 s0, 0x1c000
	s_nop 0
	v_addc_co_u32_e32 v135, vcc, 0, v133, vcc
	v_add_co_u32_e32 v136, vcc, s0, v132
	s_mov_b32 s0, 0x1d000
	s_nop 0
	v_addc_co_u32_e32 v137, vcc, 0, v133, vcc
	global_store_dword v[136:137], v72, off offset:-4096
	global_store_dword v[134:135], v73, off offset:2048
	global_store_dword v[136:137], v74, off
	global_store_dword v[136:137], v75, off offset:2048
	v_add_co_u32_e32 v134, vcc, s0, v132
	s_mov_b32 s0, 0x1e000
	s_nop 0
	v_addc_co_u32_e32 v135, vcc, 0, v133, vcc
	v_add_co_u32_e32 v136, vcc, s0, v132
	s_nop 1
	v_addc_co_u32_e32 v137, vcc, 0, v133, vcc
	v_add_co_u32_e32 v132, vcc, 0x1f000, v132
	global_store_dword v[136:137], v76, off offset:-4096
	global_store_dword v[134:135], v77, off offset:2048
	global_store_dword v[136:137], v78, off
	global_store_dword v[136:137], v79, off offset:2048
	v_addc_co_u32_e32 v133, vcc, 0, v133, vcc
	global_store_dword v[132:133], v80, off
	global_store_dword v[132:133], v81, off offset:2048
	s_mov_b64 exec, s[100:101]
	s_waitcnt vmcnt(0)
	s_waitcnt vmcnt(63) expcnt(7) lgkmcnt(15)
	s_barrier
	s_and_saveexec_b64 s[0:1], s[38:39]
	s_cbranch_execz .LBB0_633
	s_mov_b64 s[2:3], exec
	buffer_wbl2 sc1
	s_waitcnt vmcnt(0)
	buffer_inv sc1
	s_waitcnt vmcnt(0)
	v_mbcnt_lo_u32_b32 v0, s2, 0
	v_mbcnt_hi_u32_b32 v0, s3, v0
	v_cmp_eq_u32_e32 vcc, 0, v0
	s_and_saveexec_b64 s[6:7], vcc
	s_cbranch_execz .LBB0_630
	s_ashr_i32 s5, s4, 31
	s_lshl_b64 s[46:47], s[4:5], 2
	s_add_u32 s46, s18, s46
	s_addc_u32 s47, s19, s47
	s_bcnt1_i32_b64 s2, s[2:3]
	v_mov_b32_e32 v132, s2
	global_atomic_add v132, v1, v132, s[46:47] sc0

.LBB0_633:
	s_or_b64 exec, exec, s[0:1]
	s_waitcnt lgkmcnt(0)
	s_barrier
	ds_read_b32 v0, v178
	s_mov_b64 s[0:1], 0
	s_mov_b64 s[2:3], 0
	s_waitcnt lgkmcnt(0)
	v_cmp_eq_u32_e32 vcc, 0, v0
	s_cbranch_vccnz .LBB0_639
	v_readfirstlane_b32 s98, v208
	s_bitcmp1_b32 s98, 8
	s_cbranch_scc1 .LBB0_638
	s_add_u32 s2, s90, s41
	s_addc_u32 s3, s91, s40
	v_lshl_add_u64 v[130:131], v[130:131], 2, s[2:3]
	s_mov_b64 s[2:3], 0
	v_mov_b32_e32 v0, s37
	s_branch .LBB0_636

.Lskh1_a:
	s_ashr_i32 s5, s4, 31
	s_lshl_b64 s[8:9], s[4:5], 19
	s_add_u32 s1, s64, s8
	v_readlane_b32 s2, v239, 20
	s_addc_u32 s7, s2, s9
	s_lshl_b32 s14, s33, 15
	s_lshl_b64 s[2:3], s[14:15], 2
	s_waitcnt vmcnt(7)
	v_mov_b32_e32 v130, v208
	s_add_u32 s2, s1, s2
	s_addc_u32 s3, s7, s3
	v_ashrrev_i32_e32 v131, 31, v130
	v_lshl_add_u64 v[132:133], v[130:131], 2, s[2:3]
	s_movk_i32 s1, 0x1000
	s_waitcnt vmcnt(3)
	v_add_co_u32_e32 v134, vcc, s1, v132
	s_movk_i32 s1, 0x2000
	s_nop 0
	v_addc_co_u32_e32 v135, vcc, 0, v133, vcc
	v_add_co_u32_e32 v136, vcc, s1, v132
	s_movk_i32 s1, 0x3000
	s_nop 0
	v_addc_co_u32_e32 v137, vcc, 0, v133, vcc
	global_store_dword v[132:133], v114, off
	global_store_dword v[132:133], v115, off offset:2048
	global_store_dword v[136:137], v116, off offset:-4096
	global_store_dword v[134:135], v117, off offset:2048
	global_store_dword v[136:137], v118, off
	global_store_dword v[136:137], v119, off offset:2048
	v_add_co_u32_e32 v134, vcc, s1, v132
	s_movk_i32 s1, 0x4000
	s_nop 0
	v_addc_co_u32_e32 v135, vcc, 0, v133, vcc
	v_add_co_u32_e32 v136, vcc, s1, v132
	s_movk_i32 s1, 0x5000
	s_nop 0
	v_addc_co_u32_e32 v137, vcc, 0, v133, vcc
	global_store_dword v[136:137], v120, off offset:-4096
	global_store_dword v[134:135], v121, off offset:2048
	global_store_dword v[136:137], v122, off
	global_store_dword v[136:137], v123, off offset:2048
	v_add_co_u32_e32 v134, vcc, s1, v132
	s_movk_i32 s1, 0x6000
	s_nop 0
	v_addc_co_u32_e32 v135, vcc, 0, v133, vcc
	v_add_co_u32_e32 v136, vcc, s1, v132
	s_movk_i32 s1, 0x7000
	s_nop 0
	v_addc_co_u32_e32 v137, vcc, 0, v133, vcc
	global_store_dword v[136:137], v124, off offset:-4096
	global_store_dword v[134:135], v125, off offset:2048
	global_store_dword v[136:137], v126, off
	global_store_dword v[136:137], v127, off offset:2048
	v_add_co_u32_e32 v134, vcc, s1, v132
	s_mov_b32 s1, 0x8000
	s_nop 0
	v_addc_co_u32_e32 v135, vcc, 0, v133, vcc
	v_add_co_u32_e32 v136, vcc, s1, v132
	s_mov_b32 s1, 0x9000
	s_nop 0
	v_addc_co_u32_e32 v137, vcc, 0, v133, vcc
	global_store_dword v[136:137], v128, off offset:-4096
	global_store_dword v[134:135], v129, off offset:2048
	global_store_dword v[136:137], v98, off
	global_store_dword v[136:137], v99, off offset:2048
	v_add_co_u32_e32 v134, vcc, s1, v132
	s_mov_b32 s1, 0xa000
	s_nop 0
	v_addc_co_u32_e32 v135, vcc, 0, v133, vcc
	v_add_co_u32_e32 v136, vcc, s1, v132
	s_mov_b32 s1, 0xb000
	s_nop 0
	v_addc_co_u32_e32 v137, vcc, 0, v133, vcc
	global_store_dword v[136:137], v100, off offset:-4096
	global_store_dword v[134:135], v101, off offset:2048
	global_store_dword v[136:137], v102, off
	global_store_dword v[136:137], v103, off offset:2048
	v_add_co_u32_e32 v134, vcc, s1, v132
	s_mov_b32 s1, 0xc000
	s_nop 0
	v_addc_co_u32_e32 v135, vcc, 0, v133, vcc
	v_add_co_u32_e32 v136, vcc, s1, v132
	s_mov_b32 s1, 0xd000
	s_nop 0
	v_addc_co_u32_e32 v137, vcc, 0, v133, vcc
	global_store_dword v[136:137], v104, off offset:-4096
	global_store_dword v[134:135], v105, off offset:2048
	global_store_dword v[136:137], v106, off
	global_store_dword v[136:137], v107, off offset:2048
	v_add_co_u32_e32 v134, vcc, s1, v132
	s_mov_b32 s1, 0xe000
	s_nop 0
	v_addc_co_u32_e32 v135, vcc, 0, v133, vcc
	v_add_co_u32_e32 v136, vcc, s1, v132
	s_mov_b32 s1, 0xf000
	s_nop 0
	v_addc_co_u32_e32 v137, vcc, 0, v133, vcc
	global_store_dword v[136:137], v108, off offset:-4096
	global_store_dword v[134:135], v109, off offset:2048
	global_store_dword v[136:137], v110, off
	global_store_dword v[136:137], v111, off offset:2048
	v_add_co_u32_e32 v134, vcc, s1, v132
	s_mov_b32 s1, 0x10000
	s_nop 0
	v_addc_co_u32_e32 v135, vcc, 0, v133, vcc
	v_add_co_u32_e32 v136, vcc, s1, v132
	s_mov_b32 s1, 0x11000
	s_nop 0
	v_addc_co_u32_e32 v137, vcc, 0, v133, vcc
	global_store_dword v[136:137], v112, off offset:-4096
	global_store_dword v[134:135], v113, off offset:2048
	global_store_dword v[136:137], v82, off
	global_store_dword v[136:137], v83, off offset:2048
	v_add_co_u32_e32 v134, vcc, s1, v132
	s_mov_b32 s1, 0x12000
	s_nop 0
	v_addc_co_u32_e32 v135, vcc, 0, v133, vcc
	v_add_co_u32_e32 v136, vcc, s1, v132
	s_mov_b32 s1, 0x13000
	s_nop 0
	v_addc_co_u32_e32 v137, vcc, 0, v133, vcc
	global_store_dword v[136:137], v84, off offset:-4096
	global_store_dword v[134:135], v85, off offset:2048
	global_store_dword v[136:137], v86, off
	global_store_dword v[136:137], v87, off offset:2048
	v_add_co_u32_e32 v134, vcc, s1, v132
	s_mov_b32 s1, 0x14000
	s_nop 0
	v_addc_co_u32_e32 v135, vcc, 0, v133, vcc
	v_add_co_u32_e32 v136, vcc, s1, v132
	s_mov_b32 s1, 0x15000
	s_nop 0
	v_addc_co_u32_e32 v137, vcc, 0, v133, vcc
	global_store_dword v[136:137], v88, off offset:-4096
	global_store_dword v[134:135], v89, off offset:2048
	global_store_dword v[136:137], v90, off
	global_store_dword v[136:137], v91, off offset:2048
	v_add_co_u32_e32 v134, vcc, s1, v132
	s_mov_b32 s1, 0x16000
	s_nop 0
	v_addc_co_u32_e32 v135, vcc, 0, v133, vcc
	v_add_co_u32_e32 v136, vcc, s1, v132
	s_mov_b32 s1, 0x17000
	s_nop 0
	v_addc_co_u32_e32 v137, vcc, 0, v133, vcc
	global_store_dword v[136:137], v92, off offset:-4096
	global_store_dword v[134:135], v93, off offset:2048
	global_store_dword v[136:137], v94, off
	global_store_dword v[136:137], v95, off offset:2048
	v_add_co_u32_e32 v134, vcc, s1, v132
	s_mov_b32 s1, 0x18000
	s_nop 0
	v_addc_co_u32_e32 v135, vcc, 0, v133, vcc
	v_add_co_u32_e32 v136, vcc, s1, v132
	s_mov_b32 s1, 0x19000
	s_nop 0
	v_addc_co_u32_e32 v137, vcc, 0, v133, vcc
	global_store_dword v[136:137], v96, off offset:-4096
	global_store_dword v[134:135], v97, off offset:2048
	global_store_dword v[136:137], v66, off
	global_store_dword v[136:137], v67, off offset:2048
	v_add_co_u32_e32 v134, vcc, s1, v132
	s_mov_b32 s1, 0x1a000
	s_nop 0
	v_addc_co_u32_e32 v135, vcc, 0, v133, vcc
	v_add_co_u32_e32 v136, vcc, s1, v132
	s_mov_b32 s1, 0x1b000
	s_nop 0
	v_addc_co_u32_e32 v137, vcc, 0, v133, vcc
	global_store_dword v[136:137], v68, off offset:-4096
	global_store_dword v[134:135], v69, off offset:2048
	global_store_dword v[136:137], v70, off
	global_store_dword v[136:137], v71, off offset:2048
	v_add_co_u32_e32 v134, vcc, s1, v132
	s_mov_b32 s1, 0x1c000
	s_nop 0
	v_addc_co_u32_e32 v135, vcc, 0, v133, vcc
	v_add_co_u32_e32 v136, vcc, s1, v132
	s_mov_b32 s1, 0x1d000
	s_nop 0
	v_addc_co_u32_e32 v137, vcc, 0, v133, vcc
	global_store_dword v[136:137], v72, off offset:-4096
	global_store_dword v[134:135], v73, off offset:2048
	global_store_dword v[136:137], v74, off
	global_store_dword v[136:137], v75, off offset:2048
	v_add_co_u32_e32 v134, vcc, s1, v132
	s_mov_b32 s1, 0x1e000
	s_nop 0
	v_addc_co_u32_e32 v135, vcc, 0, v133, vcc
	v_add_co_u32_e32 v136, vcc, s1, v132
	s_nop 1
	v_addc_co_u32_e32 v137, vcc, 0, v133, vcc
	v_add_co_u32_e32 v132, vcc, 0x1f000, v132
	global_store_dword v[136:137], v76, off offset:-4096
	global_store_dword v[134:135], v77, off offset:2048
	global_store_dword v[136:137], v78, off
	global_store_dword v[136:137], v79, off offset:2048
	v_addc_co_u32_e32 v133, vcc, 0, v133, vcc
	global_store_dword v[132:133], v80, off
	global_store_dword v[132:133], v81, off offset:2048
	s_mov_b64 exec, s[100:101]
	s_waitcnt vmcnt(0)
	s_waitcnt vmcnt(63) expcnt(7) lgkmcnt(15)
	s_barrier
	s_and_saveexec_b64 s[2:3], s[38:39]
	s_cbranch_execz .LBB0_3615
	s_mov_b64 s[10:11], exec
	buffer_wbl2 sc1
	s_waitcnt vmcnt(0)
	buffer_inv sc1
	s_waitcnt vmcnt(0)
	v_mbcnt_lo_u32_b32 v0, s10, 0
	v_mbcnt_hi_u32_b32 v0, s11, v0
	v_cmp_eq_u32_e32 vcc, 0, v0
	s_and_saveexec_b64 s[22:23], vcc
	s_cbranch_execz .LBB0_3612
	s_lshl_b64 s[24:25], s[4:5], 2
	v_readlane_b32 s1, v239, 27
	s_add_u32 s24, s1, s24
	v_readlane_b32 s1, v239, 28
	s_addc_u32 s25, s1, s25
	s_bcnt1_i32_b64 s1, s[10:11]
	v_mov_b32_e32 v132, s1
	global_atomic_add v132, v1, v132, s[24:25] sc0

.LBB0_3615:
	s_or_b64 exec, exec, s[2:3]
	s_waitcnt lgkmcnt(0)
	s_barrier
	ds_read_b32 v0, v180
	s_mov_b64 s[2:3], 0
	s_mov_b64 s[10:11], 0
	s_waitcnt lgkmcnt(0)
	v_cmp_eq_u32_e32 vcc, 0, v0
	s_cbranch_vccnz .LBB0_3621
	v_readfirstlane_b32 s98, v208
	s_bitcmp1_b32 s98, 8
	s_cbranch_scc1 .LBB0_3620
	s_add_u32 s8, s90, s8
	s_addc_u32 s9, s91, s9
	v_lshl_add_u64 v[130:131], v[130:131], 2, s[8:9]
	s_mov_b64 s[8:9], 0
	v_mov_b32_e32 v0, s33
	s_branch .LBB0_3618

.Lskh2_a:
	s_mul_i32 s84, s4, 0x160000
	s_mul_hi_i32 s64, s4, 0x160000
	s_add_u32 s2, s65, s84
	v_readlane_b32 s0, v239, 20
	s_addc_u32 s3, s0, s64
	s_lshl_b32 s14, s55, 15
	s_lshl_b64 s[0:1], s[14:15], 2
	s_waitcnt vmcnt(7)
	v_mov_b32_e32 v130, v208
	s_add_u32 s0, s2, s0
	s_addc_u32 s1, s3, s1
	v_ashrrev_i32_e32 v131, 31, v130
	v_lshl_add_u64 v[132:133], v[130:131], 2, s[0:1]
	s_movk_i32 s0, 0x1000
	s_waitcnt vmcnt(3)
	v_add_co_u32_e32 v134, vcc, s0, v132
	s_movk_i32 s0, 0x2000
	s_nop 0
	v_addc_co_u32_e32 v135, vcc, 0, v133, vcc
	v_add_co_u32_e32 v136, vcc, s0, v132
	s_movk_i32 s0, 0x3000
	s_nop 0
	v_addc_co_u32_e32 v137, vcc, 0, v133, vcc
	global_store_dword v[132:133], v114, off
	global_store_dword v[132:133], v115, off offset:2048
	global_store_dword v[136:137], v116, off offset:-4096
	global_store_dword v[134:135], v117, off offset:2048
	global_store_dword v[136:137], v118, off
	global_store_dword v[136:137], v119, off offset:2048
	v_add_co_u32_e32 v134, vcc, s0, v132
	s_movk_i32 s0, 0x4000
	s_nop 0
	v_addc_co_u32_e32 v135, vcc, 0, v133, vcc
	v_add_co_u32_e32 v136, vcc, s0, v132
	s_movk_i32 s0, 0x5000
	s_nop 0
	v_addc_co_u32_e32 v137, vcc, 0, v133, vcc
	global_store_dword v[136:137], v120, off offset:-4096
	global_store_dword v[134:135], v121, off offset:2048
	global_store_dword v[136:137], v122, off
	global_store_dword v[136:137], v123, off offset:2048
	v_add_co_u32_e32 v134, vcc, s0, v132
	s_movk_i32 s0, 0x6000
	s_nop 0
	v_addc_co_u32_e32 v135, vcc, 0, v133, vcc
	v_add_co_u32_e32 v136, vcc, s0, v132
	s_movk_i32 s0, 0x7000
	s_nop 0
	v_addc_co_u32_e32 v137, vcc, 0, v133, vcc
	global_store_dword v[136:137], v124, off offset:-4096
	global_store_dword v[134:135], v125, off offset:2048
	global_store_dword v[136:137], v126, off
	global_store_dword v[136:137], v127, off offset:2048
	v_add_co_u32_e32 v134, vcc, s0, v132
	s_mov_b32 s0, 0x8000
	s_nop 0
	v_addc_co_u32_e32 v135, vcc, 0, v133, vcc
	v_add_co_u32_e32 v136, vcc, s0, v132
	s_mov_b32 s0, 0x9000
	s_nop 0
	v_addc_co_u32_e32 v137, vcc, 0, v133, vcc
	global_store_dword v[136:137], v128, off offset:-4096
	global_store_dword v[134:135], v129, off offset:2048
	global_store_dword v[136:137], v98, off
	global_store_dword v[136:137], v99, off offset:2048
	v_add_co_u32_e32 v134, vcc, s0, v132
	s_mov_b32 s0, 0xa000
	s_nop 0
	v_addc_co_u32_e32 v135, vcc, 0, v133, vcc
	v_add_co_u32_e32 v136, vcc, s0, v132
	s_mov_b32 s0, 0xb000
	s_nop 0
	v_addc_co_u32_e32 v137, vcc, 0, v133, vcc
	global_store_dword v[136:137], v100, off offset:-4096
	global_store_dword v[134:135], v101, off offset:2048
	global_store_dword v[136:137], v102, off
	global_store_dword v[136:137], v103, off offset:2048
	v_add_co_u32_e32 v134, vcc, s0, v132
	s_mov_b32 s0, 0xc000
	s_nop 0
	v_addc_co_u32_e32 v135, vcc, 0, v133, vcc
	v_add_co_u32_e32 v136, vcc, s0, v132
	s_mov_b32 s0, 0xd000
	s_nop 0
	v_addc_co_u32_e32 v137, vcc, 0, v133, vcc
	global_store_dword v[136:137], v104, off offset:-4096
	global_store_dword v[134:135], v105, off offset:2048
	global_store_dword v[136:137], v106, off
	global_store_dword v[136:137], v107, off offset:2048
	v_add_co_u32_e32 v134, vcc, s0, v132
	s_mov_b32 s0, 0x12000
	s_nop 0
	v_addc_co_u32_e32 v135, vcc, 0, v133, vcc
	v_add_co_u32_e32 v136, vcc, s28, v132
	s_nop 1
	v_addc_co_u32_e32 v137, vcc, 0, v133, vcc
	global_store_dword v[136:137], v108, off offset:-4096
	global_store_dword v[134:135], v109, off offset:2048
	global_store_dword v[136:137], v110, off
	global_store_dword v[136:137], v111, off offset:2048
	v_add_co_u32_e32 v134, vcc, s29, v132
	s_nop 1
	v_addc_co_u32_e32 v135, vcc, 0, v133, vcc
	v_add_co_u32_e32 v136, vcc, s30, v132
	s_nop 1
	v_addc_co_u32_e32 v137, vcc, 0, v133, vcc
	global_store_dword v[136:137], v112, off offset:-4096
	global_store_dword v[134:135], v113, off offset:2048
	global_store_dword v[136:137], v82, off
	global_store_dword v[136:137], v83, off offset:2048
	v_add_co_u32_e32 v134, vcc, s31, v132
	s_nop 1
	v_addc_co_u32_e32 v135, vcc, 0, v133, vcc
	v_add_co_u32_e32 v136, vcc, s0, v132
	s_nop 1
	v_addc_co_u32_e32 v137, vcc, 0, v133, vcc
	global_store_dword v[136:137], v84, off offset:-4096
	global_store_dword v[134:135], v85, off offset:2048
	global_store_dword v[136:137], v86, off
	global_store_dword v[136:137], v87, off offset:2048
	v_add_co_u32_e32 v134, vcc, s34, v132
	s_nop 1
	v_addc_co_u32_e32 v135, vcc, 0, v133, vcc
	v_add_co_u32_e32 v136, vcc, s35, v132
	s_nop 1
	v_addc_co_u32_e32 v137, vcc, 0, v133, vcc
	global_store_dword v[136:137], v88, off offset:-4096
	global_store_dword v[134:135], v89, off offset:2048
	global_store_dword v[136:137], v90, off
	global_store_dword v[136:137], v91, off offset:2048
	v_add_co_u32_e32 v134, vcc, s36, v132
	s_nop 1
	v_addc_co_u32_e32 v135, vcc, 0, v133, vcc
	v_add_co_u32_e32 v136, vcc, s37, v132
	s_nop 1
	v_addc_co_u32_e32 v137, vcc, 0, v133, vcc
	global_store_dword v[136:137], v92, off offset:-4096
	global_store_dword v[134:135], v93, off offset:2048
	global_store_dword v[136:137], v94, off
	global_store_dword v[136:137], v95, off offset:2048
	v_add_co_u32_e32 v134, vcc, s40, v132
	s_nop 1
	v_addc_co_u32_e32 v135, vcc, 0, v133, vcc
	v_add_co_u32_e32 v136, vcc, s41, v132
	s_nop 1
	v_addc_co_u32_e32 v137, vcc, 0, v133, vcc
	global_store_dword v[136:137], v96, off offset:-4096
	global_store_dword v[134:135], v97, off offset:2048
	global_store_dword v[136:137], v66, off
	global_store_dword v[136:137], v67, off offset:2048
	v_add_co_u32_e32 v134, vcc, s46, v132
	s_nop 1
	v_addc_co_u32_e32 v135, vcc, 0, v133, vcc
	v_add_co_u32_e32 v136, vcc, s47, v132
	s_nop 1
	v_addc_co_u32_e32 v137, vcc, 0, v133, vcc
	global_store_dword v[136:137], v68, off offset:-4096
	global_store_dword v[134:135], v69, off offset:2048
	global_store_dword v[136:137], v70, off
	global_store_dword v[136:137], v71, off offset:2048
	v_add_co_u32_e32 v134, vcc, s48, v132
	s_nop 1
	v_addc_co_u32_e32 v135, vcc, 0, v133, vcc
	v_add_co_u32_e32 v136, vcc, s49, v132
	s_nop 1
	v_addc_co_u32_e32 v137, vcc, 0, v133, vcc
	global_store_dword v[136:137], v72, off offset:-4096
	global_store_dword v[134:135], v73, off offset:2048
	global_store_dword v[136:137], v74, off
	global_store_dword v[136:137], v75, off offset:2048
	v_add_co_u32_e32 v134, vcc, s50, v132
	s_nop 1
	v_addc_co_u32_e32 v135, vcc, 0, v133, vcc
	v_add_co_u32_e32 v136, vcc, s51, v132
	s_nop 1
	v_addc_co_u32_e32 v137, vcc, 0, v133, vcc
	v_add_co_u32_e32 v132, vcc, 0x1f000, v132
	global_store_dword v[136:137], v76, off offset:-4096
	global_store_dword v[134:135], v77, off offset:2048
	global_store_dword v[136:137], v78, off
	global_store_dword v[136:137], v79, off offset:2048
	v_addc_co_u32_e32 v133, vcc, 0, v133, vcc
	global_store_dword v[132:133], v80, off
	global_store_dword v[132:133], v81, off offset:2048
	s_mov_b64 exec, s[100:101]
	s_waitcnt vmcnt(0)
	s_waitcnt vmcnt(63) expcnt(7) lgkmcnt(15)
	s_barrier
	s_and_saveexec_b64 s[0:1], s[38:39]
	s_cbranch_execz .LBB0_4585
	s_mov_b64 s[2:3], exec
	buffer_wbl2 sc1
	s_waitcnt vmcnt(0)
	buffer_inv sc1
	s_waitcnt vmcnt(0)
	v_mbcnt_lo_u32_b32 v0, s2, 0
	v_mbcnt_hi_u32_b32 v0, s3, v0
	v_cmp_eq_u32_e32 vcc, 0, v0
	s_and_saveexec_b64 s[6:7], vcc
	s_cbranch_execz .LBB0_4582
	s_ashr_i32 s5, s4, 31
	s_lshl_b64 s[86:87], s[4:5], 2
	s_add_u32 s86, s20, s86
	s_addc_u32 s87, s21, s87
	s_bcnt1_i32_b64 s2, s[2:3]
	v_mov_b32_e32 v132, s2
	global_atomic_add v132, v1, v132, s[86:87] sc0

.LBB0_4585:
	s_or_b64 exec, exec, s[0:1]
	s_waitcnt lgkmcnt(0)
	s_barrier
	ds_read_b32 v0, v178
	s_mov_b64 s[0:1], 0
	s_mov_b64 s[2:3], 0
	s_waitcnt lgkmcnt(0)
	v_cmp_eq_u32_e32 vcc, 0, v0
	s_cbranch_vccnz .LBB0_4591
	v_readfirstlane_b32 s98, v208
	s_bitcmp1_b32 s98, 8
	s_cbranch_scc1 .LBB0_4590
	s_add_u32 s2, s90, s84
	s_addc_u32 s3, s91, s64
	v_lshl_add_u64 v[130:131], v[130:131], 2, s[2:3]
	s_mov_b64 s[2:3], 0
	v_mov_b32_e32 v0, s55
	s_branch .LBB0_4588
